# P1 GEMM incremental epilogue: three quarters of each tile converted and stored inside the next tile's peeled first body
# speedup vs baseline: 1.0089x; 1.0029x over previous
; #define PG8_STAGE(bufoff, gbase, voff) do { _Pragma("unroll") for (int _i = 0; _i < 2; ++_i) \
;         __builtin_amdgcn_global_load_lds((const unsigned*)((const char*)(gbase) + (voff)[_i]), (LAS unsigned*)(lds + (bufoff) + ldsw + _i * 8192), 16, 0, 0); } while (0)
; #define PG8_WAIT_V(n) asm volatile("s_waitcnt vmcnt(" #n ")" ::: "memory")
; #define PG8_BAR __builtin_amdgcn_s_barrier()
; #define PG8_WAIT_V(n) asm volatile("s_waitcnt vmcnt(" #n ")" ::: "memory")
; #define PG8_BAR __builtin_amdgcn_s_barrier()
; template <class Epi, bool AFTER = false>
; __device__ __forceinline__ void gemm_phase(LAS unsigned char* lds, const Gemm g, const StaticOrder& S, const Epi& E) {
;     const int tid = threadIdx.x, wid = __builtin_amdgcn_readfirstlane(tid >> 6), lane = tid & 63, wr = wid >> 2, wc = wid & 3, fr = lane & 15, fq = lane >> 4;
;     const int K = g.K, nt = K / BK;
;     unsigned voffA[2], voffB[2];
; #pragma unroll
;     for (int i = 0; i < 2; ++i) { int R, C; stage_rc(tid * 16 + i * 8192, R, C); const int Rb = (R & ~31) + perm32(R & 31);
;         voffA[i] = (unsigned)(R * K + C) * 2u; voffB[i] = (unsigned)(Rb * K + C) * 2u; }
;     const size_t kstep = (size_t)(BK * 2);
;     const size_t hstep = (size_t)HALF * K * 2;
;     const size_t tstep = 2 * hstep;
;     const unsigned ldsw = (unsigned)wid * 1024u;
;     const int aoff = lds_byte(wr * 64 + fr, fq * 8), boff = lds_byte(wc * 32 + fr, fq * 8);
;     ...
;     Unit cur, nxt; int ui = 0;
;     if (!S.next(0, cur)) return;
;     f32x4 acc[2][2][4][2];
; #pragma unroll
;     for (int a = 0; a < 2; ++a)
; #pragma unroll
;         for (int b = 0; b < 2; ++b)
; #pragma unroll
;             for (int m = 0; m < 4; ++m)
; #pragma unroll
;                 for (int n = 0; n < 2; ++n) acc[a][b][m][n] = (f32x4){0.f, 0.f, 0.f, 0.f};
;     bf16x8 At[4][2], B0[2][2], B1[2][2];
;     const char* cA = (const char*)g.A + (size_t)cur.pm * tstep; const char* cB = (const char*)g.Bt + (size_t)cur.pn * tstep;
;     PG8_STAGE(PG8_SB(0, 0), cB, voffB); PG8_STAGE(PG8_SA(0, 0), cA, voffA); PG8_STAGE(PG8_SB(0, 1), cB + hstep, voffB); PG8_STAGE(PG8_SA(0, 1), cA + hstep, voffA);
;     if (wr == 1) PG8_BAR;
;     PG8_WAIT_V(4); PG8_BAR;
;     PG8_STAGE(PG8_SB(1, 0), cB + kstep, voffB); PG8_STAGE(PG8_SA(1, 0), cA + kstep, voffA); PG8_STAGE(PG8_SB(1, 1), cB + hstep + kstep, voffB);
;     PG8_WAIT_V(6); PG8_BAR;
.LBB0_110:
	s_cmp_lt_i32 s90, 2
	s_cselect_b64 s[2:3], -1, 0
	s_add_u32 s4, s88, 0x1d80000
	s_addc_u32 s5, s89, 0
	s_and_b64 s[0:1], s[2:3], s[0:1]
	v_writelane_b32 v254, s4, 20
	s_andn2_b64 vcc, exec, s[0:1]
	s_nop 0
	v_writelane_b32 v254, s5, 21
	s_cbranch_vccnz .LBB0_123
	s_cmpk_gt_i32 s84, 0x4ff
	v_readfirstlane_b32 s22, v212
	s_cbranch_scc1 .LBB0_123
	v_lshrrev_b32_e32 v2, 1, v212
	v_and_b32_e32 v11, 24, v2
	v_lshrrev_b32_e32 v2, 5, v212
	v_and_b32_e32 v2, 4, v2
	v_bfe_u32 v3, v212, 2, 2
	v_lshlrev_b32_e32 v0, 4, v212
	v_and_b32_e32 v1, 32, v212
	v_bfe_u32 v10, v212, 2, 4
	v_or3_b32 v2, v2, v3, v11
	v_lshrrev_b32_e32 v3, 3, v212
	s_movk_i32 s2, 0x70
	v_bitop3_b32 v8, v0, v1, 48 bitop3:0x6c
	v_and_b32_e32 v9, 64, v212
	v_and_or_b32 v4, v3, s2, v10
	s_movk_i32 s2, 0x60
	v_add_u32_e32 v12, 0x2000, v0
	v_or_b32_e32 v1, v8, v9
	v_and_or_b32 v3, v3, s2, v2
	v_lshrrev_b32_e32 v0, 7, v12
	s_movk_i32 s2, 0xf0
	v_lshl_or_b32 v130, v3, 11, v1
	v_and_or_b32 v3, v0, s2, v10
	s_movk_i32 s2, 0xe0
	s_ashr_i32 s24, s84, 31
	v_and_or_b32 v0, v0, s2, v2
	s_lshr_b32 s2, s24, 29
	s_add_i32 s2, s84, s2
	s_lshr_b32 s4, s22, 6
	s_ashr_i32 s5, s2, 3
	s_and_b32 s2, s2, -8
	s_lshr_b32 s3, s22, 8
	s_lshl_b32 s23, s4, 10
	s_sub_i32 s2, s84, s2
	s_cmp_lt_i32 s2, 0
	s_movk_i32 s25, 0xa1
	s_cselect_b32 s6, s25, 0xa0
	s_mul_i32 s2, s2, s6
	s_add_i32 s2, s2, s5
	s_mul_hi_i32 s5, s2, 0x66666667
	s_lshr_b32 s6, s5, 31
	s_ashr_i32 s5, s5, 5
	s_add_i32 s5, s5, s6
	s_lshl_b32 s6, s5, 2
	s_mulk_i32 s5, 0x50
	s_sub_i32 s5, s2, s5
	s_bfe_i32 s2, s5, 0x80000
	s_bfe_u32 s2, s2, 0x2000d
	s_add_i32 s7, s5, s2
	s_bfe_i32 s2, s7, 0x80000
	s_and_b32 s7, s7, 0xfc
	s_sub_i32 s5, s5, s7
	s_sext_i32_i16 s2, s2
	s_sext_i32_i8 s5, s5
	s_lshr_b32 s2, s2, 2
	s_add_i32 s6, s6, s5
	s_ashr_i32 s7, s6, 31
	s_bfe_i64 s[10:11], s[2:3], 0x100000
	s_lshl_b64 s[8:9], s[6:7], 19
	s_lshl_b64 s[10:11], s[10:11], 19
	s_add_u32 s18, s88, s10
	s_addc_u32 s19, s89, s11
	s_add_i32 s7, s23, 0
	s_add_i32 m0, s7, 0x10000
	v_lshl_or_b32 v134, v0, 11, v1
	global_load_lds_dwordx4 v130, s[18:19]
	s_add_i32 m0, s7, 0x12000
	s_add_u32 s16, s74, s8
	v_lshl_or_b32 v128, v4, 11, v1
	global_load_lds_dwordx4 v134, s[18:19]
	s_addc_u32 s17, s75, s9
	s_mov_b32 m0, s7
	s_add_i32 s26, s7, 0x2000
	v_lshl_or_b32 v132, v3, 11, v1
	global_load_lds_dwordx4 v128, s[16:17]
	s_mov_b32 m0, s26
	s_add_u32 s8, s18, 0x40000
	global_load_lds_dwordx4 v132, s[16:17]
	s_addc_u32 s9, s19, 0
	s_add_i32 m0, s7, 0x14000
	v_mov_b32_e32 v131, 0
	global_load_lds_dwordx4 v130, s[8:9]
	s_add_i32 m0, s7, 0x16000
	v_mov_b32_e32 v135, v131
	global_load_lds_dwordx4 v134, s[8:9]
	s_add_u32 s8, s16, 0x40000
	s_addc_u32 s9, s17, 0
	s_add_i32 s27, s7, 0x4000
	s_mov_b32 m0, s27
	s_add_i32 s28, s7, 0x6000
	global_load_lds_dwordx4 v128, s[8:9]
	s_mov_b32 m0, s28
	s_waitcnt lgkmcnt(0)
	v_mov_b32_e32 v129, v131
	global_load_lds_dwordx4 v132, s[8:9]
	v_mov_b32_e32 v133, v131
	s_mov_b32 s29, 0
	s_mov_b32 s100, 0
	v_lshl_add_u64 v[6:7], s[18:19], 0, v[130:131]
	v_lshl_add_u64 v[4:5], s[18:19], 0, v[134:135]
	v_lshl_add_u64 v[2:3], s[16:17], 0, v[128:129]
	s_cmp_lg_u32 s3, 1
	v_lshl_add_u64 v[0:1], s[16:17], 0, v[132:133]
	s_cbranch_scc1 .LBB0_114
	s_barrier

; #define PG8_STAGE(bufoff, gbase, voff) do { _Pragma("unroll") for (int _i = 0; _i < 2; ++_i) \
;         __builtin_amdgcn_global_load_lds((const unsigned*)((const char*)(gbase) + (voff)[_i]), (LAS unsigned*)(lds + (bufoff) + ldsw + _i * 8192), 16, 0, 0); } while (0)
; #define PG8_LDA(dst, b, h) do { _Pragma("unroll") for (int m = 0; m < 4; ++m) _Pragma("unroll") for (int k = 0; k < 2; ++k) dst[m][k] = *(const LAS bf16x8*)(lds + PG8_SA(b, h) + aoff + m * 2048 + k * 1024); } while (0)
; #define PG8_LDB(dst, b, h) do { _Pragma("unroll") for (int n = 0; n < 2; ++n) _Pragma("unroll") for (int k = 0; k < 2; ++k) dst[n][k] = *(const LAS bf16x8*)(lds + PG8_SB(b, h) + boff + n * 2048 + k * 1024); } while (0)
; #define PG8_WAIT_L(n) asm volatile("s_waitcnt lgkmcnt(" #n ")" ::: "memory")
; #define PG8_BAR __builtin_amdgcn_s_barrier()
; #define PG8_SCHED __builtin_amdgcn_sched_barrier(0)
;     __device__ bool next(int i, Unit& u) const {
;         const long L = (long)i * G + c; if (L >= nwg) return false;
;         int wgid = (int)L; { const int q = nwg / NXCD, r = nwg % NXCD, xcd = wgid % NXCD, off = wgid / NXCD; wgid = (xcd < r ? xcd * (q + 1) : r * (q + 1) + (xcd - r) * q) + off; }
;         const int nig = WGM * nN, gid = wgid / nig, fm = gid * WGM, gsz = (nM - fm) < WGM ? (nM - fm) : WGM;
;         u.pm = fm + ((wgid % nig) % gsz); u.pn = (wgid % nig) / gsz; return true;
; template <class Epi, bool AFTER = false>
; __device__ __forceinline__ void gemm_phase(LAS unsigned char* lds, const Gemm g, const StaticOrder& S, const Epi& E) {
;     ...
;         const bool has_next = S.next(ui + 1, nxt);
;         const char* nA = has_next ? (const char*)g.A + (size_t)nxt.pm * tstep : cA; const char* nB = has_next ? (const char*)g.Bt + (size_t)nxt.pn * tstep : cB;
;         for (int t = 0; t < nt; t += 2) {
;             const bool last = (t == nt - 2);
;             const char* a1 = cA + (size_t)(t + 1) * kstep;
;             const char* a2 = last ? nA : cA + (size_t)(t + 2) * kstep; const char* b2 = last ? nB : cB + (size_t)(t + 2) * kstep;
;             const char* a3 = a2 + kstep; const char* b3 = b2 + kstep;
;             PG8_LDB(B0, 0, 0); PG8_SCHED; PG8_LDA(At, 0, 0); PG8_STAGE(PG8_SA(1, 1), a1 + hstep, voffA);
;             PG8_WAIT_L(8); PG8_BAR; PG8_WAIT_L(0); PG8_MMA(0, 0, At, B0); PG8_BAR; PG8_SCHED;
;             PG8_LDB(B1, 0, 1); PG8_STAGE(PG8_SB(0, 0), b2, voffB);
.LBB0_115:
	s_add_i32 s29, s29, 1
	s_mul_i32 s2, s29, s30
	s_mul_hi_u32 s3, s29, s34
	s_add_i32 s3, s3, s2
	s_mul_i32 s2, s29, s34
	s_add_u32 s12, s2, s84
	s_addc_u32 s13, s3, s24
	v_cmp_gt_i64_e64 s[2:3], s[12:13], v[142:143]
	s_and_b64 vcc, exec, s[2:3]
	s_cbranch_vccnz .LBB0_117
	s_ashr_i32 s8, s12, 31
	s_lshr_b32 s8, s8, 29
	s_add_i32 s8, s12, s8
	s_ashr_i32 s9, s8, 3
	s_and_b32 s8, s8, -8
	s_sub_i32 s8, s12, s8
	s_cmp_lt_i32 s8, 0
	s_cselect_b32 s10, s25, 0xa0
	s_mul_i32 s8, s8, s10
	s_add_i32 s8, s8, s9
	s_mul_hi_i32 s9, s8, 0x66666667
	s_lshr_b32 s10, s9, 31
	s_ashr_i32 s9, s9, 5
	s_add_i32 s9, s9, s10
	s_lshl_b32 s10, s9, 2
	s_sub_i32 s11, 64, s10
	s_min_i32 s11, s11, 4
	s_abs_i32 s14, s11
	v_cvt_f32_u32_e32 v229, s14
	s_sub_i32 s20, 0, s14
	s_mulk_i32 s9, 0x50
	s_sub_i32 s9, s8, s9
	v_rcp_iflag_f32_e32 v229, v229
	s_abs_i32 s8, s9
	s_xor_b32 s15, s9, s11
	s_ashr_i32 s15, s15, 31
	v_mul_f32_e32 v229, 0x4f7ffffe, v229
	v_cvt_u32_f32_e32 v229, v229
	s_nop 0
	v_readfirstlane_b32 s21, v229
	s_mul_i32 s20, s20, s21
	s_mul_hi_u32 s20, s21, s20
	s_add_i32 s21, s21, s20
	s_mul_hi_u32 s20, s8, s21
	s_mul_i32 s21, s20, s14
	s_sub_i32 s8, s8, s21
	s_add_i32 s39, s20, 1
	s_sub_i32 s21, s8, s14
	s_cmp_ge_u32 s8, s14
	s_cselect_b32 s20, s39, s20
	s_cselect_b32 s8, s21, s8
	s_add_i32 s21, s20, 1
	s_cmp_ge_u32 s8, s14
	s_cselect_b32 s8, s21, s20
	s_xor_b32 s8, s8, s15
	s_sub_i32 s8, s8, s15
	s_mul_i32 s11, s8, s11
	s_sub_i32 s9, s9, s11
	s_add_i32 s10, s10, s9
.LBB0_117:
	s_ashr_i32 s11, s10, 31
	v_cmp_lt_i64_e32 vcc, s[12:13], v[140:141]
	s_lshl_b64 s[12:13], s[10:11], 19
	s_add_u32 s12, s74, s12
	s_addc_u32 s13, s75, s13
	s_and_b64 s[14:15], vcc, exec
	s_cselect_b32 s11, s13, s17
	s_cselect_b32 s39, s12, s16
	s_ashr_i32 s9, s8, 31
	s_lshl_b64 s[14:15], s[8:9], 19
	s_add_u32 s14, s88, s14
	s_addc_u32 s15, s89, s15
	s_and_b64 s[20:21], vcc, exec
	s_cselect_b32 s9, s15, s19
	s_cselect_b32 s40, s14, s18
	s_add_u32 s16, s16, 0x40080
	s_addc_u32 s17, s17, 0
	s_add_u32 s41, s18, 0x100
	s_addc_u32 s42, s19, 0
	s_mov_b32 s43, -2
	ds_read_b128 v[150:153], v147
	ds_read_b128 v[154:157], v147 offset:1024
	ds_read_b128 v[158:161], v147 offset:2048
	ds_read_b128 v[162:165], v147 offset:3072
	s_add_u32 s18, s16, 0xfffc0080
	s_addc_u32 s19, s17, -1
	s_cmp_eq_u32 s43, 12
	s_cselect_b32 s21, s11, s19
	s_cselect_b32 s20, s39, s18
	s_cselect_b32 s19, s9, s42
	s_cselect_b32 s18, s40, s41
	v_lshl_add_u64 v[200:201], s[16:17], 0, v[136:137]
	s_add_i32 m0, s7, 0xc000
	ds_read_b128 v[166:169], v148
	ds_read_b128 v[170:173], v148 offset:1024
	ds_read_b128 v[174:177], v148 offset:2048
	ds_read_b128 v[178:181], v148 offset:3072
	ds_read_b128 v[182:185], v148 offset:4096
	ds_read_b128 v[186:189], v148 offset:5120
	ds_read_b128 v[192:195], v148 offset:6144
	ds_read_b128 v[196:199], v148 offset:7168
	global_load_lds_dwordx4 v[200:201], off
	v_lshl_add_u64 v[200:201], s[16:17], 0, v[138:139]
	s_add_i32 m0, s7, 0xe000
	s_nop 0
	global_load_lds_dwordx4 v[200:201], off
	s_waitcnt lgkmcnt(8)
	s_barrier
	s_waitcnt lgkmcnt(0)
	s_setprio 1
	s_waitcnt lgkmcnt(0)
	v_mfma_f32_16x16x32_bf16 v[124:127], v[150:153], v[166:169], 0
	v_mfma_f32_16x16x32_bf16 v[120:123], v[158:161], v[166:169], 0
	v_mfma_f32_16x16x32_bf16 v[116:119], v[150:153], v[174:177], 0
	v_mfma_f32_16x16x32_bf16 v[112:115], v[158:161], v[174:177], 0
	v_mfma_f32_16x16x32_bf16 v[100:103], v[150:153], v[182:185], 0
	v_mfma_f32_16x16x32_bf16 v[96:99], v[158:161], v[182:185], 0
	v_mfma_f32_16x16x32_bf16 v[84:87], v[150:153], v[192:195], 0
	v_mfma_f32_16x16x32_bf16 v[80:83], v[158:161], v[192:195], 0
	v_mfma_f32_16x16x32_bf16 v[124:127], v[154:157], v[170:173], v[124:127]
	v_mfma_f32_16x16x32_bf16 v[120:123], v[162:165], v[170:173], v[120:123]
	v_mfma_f32_16x16x32_bf16 v[116:119], v[154:157], v[178:181], v[116:119]
	v_mfma_f32_16x16x32_bf16 v[112:115], v[162:165], v[178:181], v[112:115]
	v_mfma_f32_16x16x32_bf16 v[100:103], v[154:157], v[186:189], v[100:103]
	v_mfma_f32_16x16x32_bf16 v[96:99], v[162:165], v[186:189], v[96:99]
	v_mfma_f32_16x16x32_bf16 v[84:87], v[154:157], v[196:199], v[84:87]
	v_mfma_f32_16x16x32_bf16 v[80:83], v[162:165], v[196:199], v[80:83]
	s_setprio 0
	s_barrier
	s_add_i32 s44, s35, s23
	v_lshl_add_u64 v[218:219], s[18:19], 0, v[130:131]
	s_mov_b32 m0, s44
	ds_read_b128 v[200:203], v149
	ds_read_b128 v[204:207], v149 offset:1024
	ds_read_b128 v[208:211], v149 offset:2048
	ds_read_b128 v[214:217], v149 offset:3072
	global_load_lds_dwordx4 v[218:219], off
	v_lshl_add_u64 v[220:221], s[18:19], 0, v[134:135]
	s_add_i32 m0, s44, 0x2000
	s_nop 0
	global_load_lds_dwordx4 v[220:221], off
	s_cmp_eq_u32 s100, 0
	s_cbranch_scc1 .Lg1_noA2
	v_cvt_pk_bf16_f32 v108, v108, v109
	v_cvt_pk_bf16_f32 v109, v110, v111
	v_cvt_pk_bf16_f32 v110, v104, v105
	v_cvt_pk_bf16_f32 v111, v106, v107
	global_store_dwordx4 v[230:231], v[108:111], off offset:256 sc1
	s_nop 1
	v_cvt_pk_bf16_f32 v92, v92, v93
	v_cvt_pk_bf16_f32 v93, v94, v95
	v_cvt_pk_bf16_f32 v94, v88, v89
	v_cvt_pk_bf16_f32 v95, v90, v91
	global_store_dwordx4 v[232:233], v[92:95], off offset:256 sc1
	s_nop 1
	v_cvt_pk_bf16_f32 v76, v76, v77
	v_cvt_pk_bf16_f32 v77, v78, v79
	v_cvt_pk_bf16_f32 v78, v72, v73
	v_cvt_pk_bf16_f32 v79, v74, v75
	global_store_dwordx4 v[234:235], v[76:79], off offset:256 sc1
	s_nop 1
	v_cvt_pk_bf16_f32 v68, v68, v69
	v_cvt_pk_bf16_f32 v69, v70, v71
	v_cvt_pk_bf16_f32 v70, v64, v65
	v_cvt_pk_bf16_f32 v71, v66, v67
	global_store_dwordx4 v[236:237], v[68:71], off offset:256 sc1
	s_nop 1
; __device__ __forceinline__ unsigned cvt_pk_bf16(float lo, float hi) { const f32x2_t f = {lo, hi}; const bf16x2_t b = __builtin_convertvector(f, bf16x2_t); return __builtin_bit_cast(unsigned, b); }
; __device__ __forceinline__ void st_wt16(void* p, u32x4 v) { asm volatile("global_store_dwordx4 %0, %1, off sc1\n\ts_nop 1" : : "v"(p), "v"(v) : "memory"); }
; __device__ __forceinline__ void st_wt16_o256(void* p, u32x4 v) { asm volatile("global_store_dwordx4 %0, %1, off offset:256 sc1\n\ts_nop 1" : : "v"(p), "v"(v) : "memory"); }
; #define PG8_STAGE(bufoff, gbase, voff) do { _Pragma("unroll") for (int _i = 0; _i < 2; ++_i) \
;         __builtin_amdgcn_global_load_lds((const unsigned*)((const char*)(gbase) + (voff)[_i]), (LAS unsigned*)(lds + (bufoff) + ldsw + _i * 8192), 16, 0, 0); } while (0)
; #define PG8_LDA(dst, b, h) do { _Pragma("unroll") for (int m = 0; m < 4; ++m) _Pragma("unroll") for (int k = 0; k < 2; ++k) dst[m][k] = *(const LAS bf16x8*)(lds + PG8_SA(b, h) + aoff + m * 2048 + k * 1024); } while (0)
; #define PG8_BAR __builtin_amdgcn_s_barrier()
; template <class Epi, bool AFTER = false>
; __device__ __forceinline__ void gemm_phase(LAS unsigned char* lds, const Gemm g, const StaticOrder& S, const Epi& E) {
;     ...
;             PG8_BAR; PG8_WAIT_L(0); PG8_MMA(0, 1, At, B1); PG8_BAR;
;             PG8_LDA(At, 0, 1); PG8_STAGE(PG8_SA(0, 0), a2, voffA);
;             PG8_BAR; PG8_WAIT_L(0); PG8_MMA(1, 0, At, B0); PG8_BAR; PG8_SCHED;
;             PG8_STAGE(PG8_SB(0, 1), b2 + hstep, voffB);
;     __device__ __forceinline__ void operator()(const f32x4 (&acc)[2][2][4][2], const pg8::Unit& u, int wr, int wc, int fr, int fq) const {
;     ...
;                 bf16_t* rp = base + (size_t)(row0 + ai * 128 + m * 16) * ld + col0;
;                 u32x4 w0, w1;
;                 w0.x = cvt_pk_bf16(acc[ai][0][m][0][0], acc[ai][0][m][0][1]); w0.y = cvt_pk_bf16(acc[ai][0][m][0][2], acc[ai][0][m][0][3]);
;                 w0.z = cvt_pk_bf16(acc[ai][0][m][1][0], acc[ai][0][m][1][1]); w0.w = cvt_pk_bf16(acc[ai][0][m][1][2], acc[ai][0][m][1][3]);
;                 w1.x = cvt_pk_bf16(acc[ai][1][m][0][0], acc[ai][1][m][0][1]); w1.y = cvt_pk_bf16(acc[ai][1][m][0][2], acc[ai][1][m][0][3]);
;                 w1.z = cvt_pk_bf16(acc[ai][1][m][1][0], acc[ai][1][m][1][1]); w1.w = cvt_pk_bf16(acc[ai][1][m][1][2], acc[ai][1][m][1][3]);
;                 st_wt16(rp, w0); st_wt16_o256(rp, w1);
.Lg1_noA2:
	s_barrier
	s_waitcnt lgkmcnt(0)
	s_setprio 1
	s_waitcnt lgkmcnt(0)
	v_mfma_f32_16x16x32_bf16 v[108:111], v[200:203], v[166:169], 0
	v_mfma_f32_16x16x32_bf16 v[104:107], v[208:211], v[166:169], 0
	v_mfma_f32_16x16x32_bf16 v[92:95], v[200:203], v[174:177], 0
	v_mfma_f32_16x16x32_bf16 v[88:91], v[208:211], v[174:177], 0
	v_mfma_f32_16x16x32_bf16 v[76:79], v[200:203], v[182:185], 0
	v_mfma_f32_16x16x32_bf16 v[72:75], v[208:211], v[182:185], 0
	v_mfma_f32_16x16x32_bf16 v[68:71], v[200:203], v[192:195], 0
	v_mfma_f32_16x16x32_bf16 v[64:67], v[208:211], v[192:195], 0
	v_mfma_f32_16x16x32_bf16 v[108:111], v[204:207], v[170:173], v[108:111]
	v_mfma_f32_16x16x32_bf16 v[104:107], v[214:217], v[170:173], v[104:107]
	v_mfma_f32_16x16x32_bf16 v[92:95], v[204:207], v[178:181], v[92:95]
	v_mfma_f32_16x16x32_bf16 v[88:91], v[214:217], v[178:181], v[88:91]
	v_mfma_f32_16x16x32_bf16 v[76:79], v[204:207], v[186:189], v[76:79]
	v_mfma_f32_16x16x32_bf16 v[72:75], v[214:217], v[186:189], v[72:75]
	v_mfma_f32_16x16x32_bf16 v[68:71], v[204:207], v[196:199], v[68:71]
	v_mfma_f32_16x16x32_bf16 v[64:67], v[214:217], v[196:199], v[64:67]
	s_setprio 0
	s_mov_b32 m0, s7
	v_lshl_add_u64 v[222:223], s[20:21], 0, v[128:129]
	s_barrier
	ds_read_b128 v[166:169], v148 offset:16384
	ds_read_b128 v[170:173], v148 offset:17408
	ds_read_b128 v[174:177], v148 offset:18432
	ds_read_b128 v[178:181], v148 offset:19456
	ds_read_b128 v[182:185], v148 offset:20480
	ds_read_b128 v[186:189], v148 offset:21504
	ds_read_b128 v[192:195], v148 offset:22528
	ds_read_b128 v[196:199], v148 offset:23552
	global_load_lds_dwordx4 v[222:223], off
	v_lshl_add_u64 v[224:225], s[20:21], 0, v[132:133]
	s_mov_b32 m0, s26
	s_nop 0
	global_load_lds_dwordx4 v[224:225], off
	s_cmp_eq_u32 s100, 0
	s_cbranch_scc1 .Lg1_noB1
	v_add_u32_e32 v229, 0x80, v228
	v_mad_i64_i32 v[238:239], s[98:99], v229, s37, v[226:227]
	v_cvt_pk_bf16_f32 v60, v60, v61
	v_cvt_pk_bf16_f32 v61, v62, v63
	v_cvt_pk_bf16_f32 v62, v56, v57
	v_cvt_pk_bf16_f32 v63, v58, v59
	global_store_dwordx4 v[238:239], v[60:63], off sc1
	s_nop 1
	v_add_u32_e32 v229, 0x90, v228
	v_mad_i64_i32 v[240:241], s[98:99], v229, s37, v[226:227]
	v_cvt_pk_bf16_f32 v52, v52, v53
	v_cvt_pk_bf16_f32 v53, v54, v55
	v_cvt_pk_bf16_f32 v54, v48, v49
	v_cvt_pk_bf16_f32 v55, v50, v51
	global_store_dwordx4 v[240:241], v[52:55], off sc1
	s_nop 1
	v_add_u32_e32 v229, 0xa0, v228
	v_mad_i64_i32 v[242:243], s[98:99], v229, s37, v[226:227]
	v_cvt_pk_bf16_f32 v36, v36, v37
	v_cvt_pk_bf16_f32 v37, v38, v39
	v_cvt_pk_bf16_f32 v38, v32, v33
	v_cvt_pk_bf16_f32 v39, v34, v35
	global_store_dwordx4 v[242:243], v[36:39], off sc1
	s_nop 1
	v_add_u32_e32 v229, 0xb0, v228
	v_mad_i64_i32 v[244:245], s[98:99], v229, s37, v[226:227]
	v_cvt_pk_bf16_f32 v20, v20, v21
	v_cvt_pk_bf16_f32 v21, v22, v23
	v_cvt_pk_bf16_f32 v22, v16, v17
	v_cvt_pk_bf16_f32 v23, v18, v19
	global_store_dwordx4 v[244:245], v[20:23], off sc1
	s_nop 1
.Lg1_noB1:
	s_barrier
	s_waitcnt lgkmcnt(0)
	s_setprio 1
	s_waitcnt lgkmcnt(0)
	v_mfma_f32_16x16x32_bf16 v[60:63], v[150:153], v[166:169], 0
	v_mfma_f32_16x16x32_bf16 v[56:59], v[158:161], v[166:169], 0
	v_mfma_f32_16x16x32_bf16 v[52:55], v[150:153], v[174:177], 0
	v_mfma_f32_16x16x32_bf16 v[48:51], v[158:161], v[174:177], 0
	v_mfma_f32_16x16x32_bf16 v[36:39], v[150:153], v[182:185], 0
	v_mfma_f32_16x16x32_bf16 v[32:35], v[158:161], v[182:185], 0
	v_mfma_f32_16x16x32_bf16 v[20:23], v[150:153], v[192:195], 0
	v_mfma_f32_16x16x32_bf16 v[16:19], v[158:161], v[192:195], 0
	v_mfma_f32_16x16x32_bf16 v[60:63], v[154:157], v[170:173], v[60:63]
	v_mfma_f32_16x16x32_bf16 v[56:59], v[162:165], v[170:173], v[56:59]
	v_mfma_f32_16x16x32_bf16 v[52:55], v[154:157], v[178:181], v[52:55]
	v_mfma_f32_16x16x32_bf16 v[48:51], v[162:165], v[178:181], v[48:51]
	v_mfma_f32_16x16x32_bf16 v[36:39], v[154:157], v[186:189], v[36:39]
	v_mfma_f32_16x16x32_bf16 v[32:35], v[162:165], v[186:189], v[32:35]
	v_mfma_f32_16x16x32_bf16 v[20:23], v[154:157], v[196:199], v[20:23]
	v_mfma_f32_16x16x32_bf16 v[16:19], v[162:165], v[196:199], v[16:19]
	s_setprio 0
	s_barrier
	s_add_u32 s44, s18, 0x40000
	s_addc_u32 s45, s19, 0
	s_add_i32 s46, s36, s23
	v_lshl_add_u64 v[150:151], s[44:45], 0, v[130:131]
	s_mov_b32 m0, s46
	s_nop 0
	global_load_lds_dwordx4 v[150:151], off
	v_lshl_add_u64 v[150:151], s[44:45], 0, v[134:135]
	s_add_i32 m0, s46, 0x2000
	s_nop 0
	global_load_lds_dwordx4 v[150:151], off
	s_cmp_eq_u32 s100, 0
	s_cbranch_scc1 .Lg1_noB2
	v_cvt_pk_bf16_f32 v44, v44, v45
	v_cvt_pk_bf16_f32 v45, v46, v47
	v_cvt_pk_bf16_f32 v46, v40, v41
	v_cvt_pk_bf16_f32 v47, v42, v43
	global_store_dwordx4 v[238:239], v[44:47], off offset:256 sc1
	s_nop 1
	v_cvt_pk_bf16_f32 v28, v28, v29
	v_cvt_pk_bf16_f32 v29, v30, v31
	v_cvt_pk_bf16_f32 v30, v24, v25
	v_cvt_pk_bf16_f32 v31, v26, v27
	global_store_dwordx4 v[240:241], v[28:31], off offset:256 sc1
	s_nop 1
	v_cvt_pk_bf16_f32 v12, v12, v13
	v_cvt_pk_bf16_f32 v13, v14, v15
	v_cvt_pk_bf16_f32 v14, v8, v9
	v_cvt_pk_bf16_f32 v15, v10, v11
	global_store_dwordx4 v[242:243], v[12:15], off offset:256 sc1
	s_nop 1
	v_cvt_pk_bf16_f32 v4, v4, v5
	v_cvt_pk_bf16_f32 v5, v6, v7
	v_cvt_pk_bf16_f32 v6, v0, v1
	v_cvt_pk_bf16_f32 v7, v2, v3
	global_store_dwordx4 v[244:245], v[4:7], off offset:256 sc1
	s_nop 1
.Lg1_noB2:
	s_cmp_eq_u32 s100, 0
	s_cbranch_scc0 .Lg1_w18
	s_waitcnt vmcnt(6)
; #define PG8_STAGE(bufoff, gbase, voff) do { _Pragma("unroll") for (int _i = 0; _i < 2; ++_i) \
;         __builtin_amdgcn_global_load_lds((const unsigned*)((const char*)(gbase) + (voff)[_i]), (LAS unsigned*)(lds + (bufoff) + ldsw + _i * 8192), 16, 0, 0); } while (0)
; #define PG8_LDA(dst, b, h) do { _Pragma("unroll") for (int m = 0; m < 4; ++m) _Pragma("unroll") for (int k = 0; k < 2; ++k) dst[m][k] = *(const LAS bf16x8*)(lds + PG8_SA(b, h) + aoff + m * 2048 + k * 1024); } while (0)
; #define PG8_LDB(dst, b, h) do { _Pragma("unroll") for (int n = 0; n < 2; ++n) _Pragma("unroll") for (int k = 0; k < 2; ++k) dst[n][k] = *(const LAS bf16x8*)(lds + PG8_SB(b, h) + boff + n * 2048 + k * 1024); } while (0)
; #define PG8_MMA(ai, bj, At, Bt) do { __builtin_amdgcn_s_setprio(1); _Pragma("unroll") for (int m = 0; m < 4; ++m) _Pragma("unroll") for (int n = 0; n < 2; ++n) _Pragma("unroll") for (int k = 0; k < 2; ++k) \
;         acc[ai][bj][m][n] = __builtin_amdgcn_mfma_f32_16x16x32_bf16(Bt[n][k], At[m][k], acc[ai][bj][m][n], 0, 0, 0); __builtin_amdgcn_s_setprio(0); } while (0)
; #define PG8_WAIT_V(n) asm volatile("s_waitcnt vmcnt(" #n ")" ::: "memory")
; #define PG8_WAIT_L(n) asm volatile("s_waitcnt lgkmcnt(" #n ")" ::: "memory")
; #define PG8_BAR __builtin_amdgcn_s_barrier()
; #define PG8_SCHED __builtin_amdgcn_sched_barrier(0)
; #define PG8_LDA(dst, b, h) do { _Pragma("unroll") for (int m = 0; m < 4; ++m) _Pragma("unroll") for (int k = 0; k < 2; ++k) dst[m][k] = *(const LAS bf16x8*)(lds + PG8_SA(b, h) + aoff + m * 2048 + k * 1024); } while (0)
; #define PG8_WAIT_V(n) asm volatile("s_waitcnt vmcnt(" #n ")" ::: "memory")
; #define PG8_WAIT_L(n) asm volatile("s_waitcnt lgkmcnt(" #n ")" ::: "memory")
; template <class Epi, bool AFTER = false>
; __device__ __forceinline__ void gemm_phase(LAS unsigned char* lds, const Gemm g, const StaticOrder& S, const Epi& E) {
;     ...
;             PG8_WAIT_V(6); PG8_BAR; PG8_MMA(1, 1, At, B1); PG8_BAR;
;             PG8_LDB(B0, 1, 0); PG8_SCHED; PG8_LDA(At, 1, 0); PG8_STAGE(PG8_SA(0, 1), a2 + hstep, voffA);
;             PG8_WAIT_L(8); PG8_BAR; PG8_WAIT_L(0); PG8_MMA(0, 0, At, B0); PG8_BAR; PG8_SCHED;
;             PG8_LDB(B1, 1, 1); PG8_STAGE(PG8_SB(1, 0), b3, voffB);
;             PG8_BAR; PG8_WAIT_L(0); PG8_MMA(0, 1, At, B1); PG8_BAR;
;             PG8_LDA(At, 1, 1); PG8_STAGE(PG8_SA(1, 0), a3, voffA);
.Lg1_w18:
	s_waitcnt vmcnt(18)
	s_barrier
	s_setprio 1
	v_mfma_f32_16x16x32_bf16 v[44:47], v[200:203], v[166:169], 0
	v_mfma_f32_16x16x32_bf16 v[40:43], v[208:211], v[166:169], 0
	v_mfma_f32_16x16x32_bf16 v[28:31], v[200:203], v[174:177], 0
	v_mfma_f32_16x16x32_bf16 v[24:27], v[208:211], v[174:177], 0
	v_mfma_f32_16x16x32_bf16 v[12:15], v[200:203], v[182:185], 0
	v_mfma_f32_16x16x32_bf16 v[8:11], v[208:211], v[182:185], 0
	v_mfma_f32_16x16x32_bf16 v[4:7], v[200:203], v[192:195], 0
	v_mfma_f32_16x16x32_bf16 v[0:3], v[208:211], v[192:195], 0
	v_mfma_f32_16x16x32_bf16 v[44:47], v[204:207], v[170:173], v[44:47]
	v_mfma_f32_16x16x32_bf16 v[40:43], v[214:217], v[170:173], v[40:43]
	v_mfma_f32_16x16x32_bf16 v[28:31], v[204:207], v[178:181], v[28:31]
	v_mfma_f32_16x16x32_bf16 v[24:27], v[214:217], v[178:181], v[24:27]
	v_mfma_f32_16x16x32_bf16 v[12:15], v[204:207], v[186:189], v[12:15]
	v_mfma_f32_16x16x32_bf16 v[8:11], v[214:217], v[186:189], v[8:11]
	v_mfma_f32_16x16x32_bf16 v[4:7], v[204:207], v[196:199], v[4:7]
	v_mfma_f32_16x16x32_bf16 v[0:3], v[214:217], v[196:199], v[0:3]
	s_setprio 0
	s_add_i32 s44, 0, 0x18000
	v_add_u32_e32 v162, s44, v145
	s_barrier
	ds_read_b128 v[150:153], v162
	ds_read_b128 v[154:157], v162 offset:1024
	ds_read_b128 v[158:161], v162 offset:2048
	ds_read_b128 v[162:165], v162 offset:3072
	s_add_u32 s20, s20, 0x40000
	s_addc_u32 s21, s21, 0
	s_mov_b32 m0, s27
	v_lshl_add_u64 v[200:201], s[20:21], 0, v[128:129]
	ds_read_b128 v[166:169], v148 offset:32768
	ds_read_b128 v[170:173], v148 offset:33792
	ds_read_b128 v[174:177], v148 offset:34816
	ds_read_b128 v[178:181], v148 offset:35840
	ds_read_b128 v[182:185], v148 offset:36864
	ds_read_b128 v[186:189], v148 offset:37888
	ds_read_b128 v[192:195], v148 offset:38912
	ds_read_b128 v[196:199], v148 offset:39936
	global_load_lds_dwordx4 v[200:201], off
	v_lshl_add_u64 v[200:201], s[20:21], 0, v[132:133]
	s_mov_b32 m0, s28
	s_nop 0
	global_load_lds_dwordx4 v[200:201], off
	s_waitcnt lgkmcnt(8)
	s_barrier
	s_waitcnt lgkmcnt(0)
	s_setprio 1
	s_waitcnt lgkmcnt(0)
	v_mfma_f32_16x16x32_bf16 v[124:127], v[150:153], v[166:169], v[124:127]
	v_mfma_f32_16x16x32_bf16 v[120:123], v[158:161], v[166:169], v[120:123]
	v_mfma_f32_16x16x32_bf16 v[116:119], v[150:153], v[174:177], v[116:119]
	v_mfma_f32_16x16x32_bf16 v[112:115], v[158:161], v[174:177], v[112:115]
	v_mfma_f32_16x16x32_bf16 v[100:103], v[150:153], v[182:185], v[100:103]
	v_mfma_f32_16x16x32_bf16 v[96:99], v[158:161], v[182:185], v[96:99]
	v_mfma_f32_16x16x32_bf16 v[84:87], v[150:153], v[192:195], v[84:87]
	v_mfma_f32_16x16x32_bf16 v[80:83], v[158:161], v[192:195], v[80:83]
	v_mfma_f32_16x16x32_bf16 v[124:127], v[154:157], v[170:173], v[124:127]
	v_mfma_f32_16x16x32_bf16 v[120:123], v[162:165], v[170:173], v[120:123]
	v_mfma_f32_16x16x32_bf16 v[116:119], v[154:157], v[178:181], v[116:119]
	v_mfma_f32_16x16x32_bf16 v[112:115], v[162:165], v[178:181], v[112:115]
	v_mfma_f32_16x16x32_bf16 v[100:103], v[154:157], v[186:189], v[100:103]
	v_mfma_f32_16x16x32_bf16 v[96:99], v[162:165], v[186:189], v[96:99]
	v_mfma_f32_16x16x32_bf16 v[84:87], v[154:157], v[196:199], v[84:87]
	v_mfma_f32_16x16x32_bf16 v[80:83], v[162:165], v[196:199], v[80:83]
	s_setprio 0
	s_barrier
	s_add_i32 s20, 0, 0x1c000
	s_add_i32 s21, s44, s23
	v_add_u32_e32 v191, s20, v145
	v_lshl_add_u64 v[218:219], v[218:219], 0, s[4:5]
	s_mov_b32 m0, s21
	ds_read_b128 v[200:203], v191
	ds_read_b128 v[204:207], v191 offset:1024
	ds_read_b128 v[208:211], v191 offset:2048
	ds_read_b128 v[214:217], v191 offset:3072
	global_load_lds_dwordx4 v[218:219], off
	v_lshl_add_u64 v[218:219], v[220:221], 0, s[4:5]
	s_add_i32 m0, s21, 0x2000
	s_nop 0
	global_load_lds_dwordx4 v[218:219], off
	s_barrier
	s_waitcnt lgkmcnt(0)
	s_setprio 1
	s_waitcnt lgkmcnt(0)
	v_mfma_f32_16x16x32_bf16 v[108:111], v[200:203], v[166:169], v[108:111]
	v_mfma_f32_16x16x32_bf16 v[104:107], v[208:211], v[166:169], v[104:107]
	v_mfma_f32_16x16x32_bf16 v[92:95], v[200:203], v[174:177], v[92:95]
	v_mfma_f32_16x16x32_bf16 v[88:91], v[208:211], v[174:177], v[88:91]
	v_mfma_f32_16x16x32_bf16 v[76:79], v[200:203], v[182:185], v[76:79]
	v_mfma_f32_16x16x32_bf16 v[72:75], v[208:211], v[182:185], v[72:75]
	v_mfma_f32_16x16x32_bf16 v[68:71], v[200:203], v[192:195], v[68:71]
	v_mfma_f32_16x16x32_bf16 v[64:67], v[208:211], v[192:195], v[64:67]
	v_mfma_f32_16x16x32_bf16 v[108:111], v[204:207], v[170:173], v[108:111]
	v_mfma_f32_16x16x32_bf16 v[104:107], v[214:217], v[170:173], v[104:107]
	v_mfma_f32_16x16x32_bf16 v[92:95], v[204:207], v[178:181], v[92:95]
	v_mfma_f32_16x16x32_bf16 v[88:91], v[214:217], v[178:181], v[88:91]
	v_mfma_f32_16x16x32_bf16 v[76:79], v[204:207], v[186:189], v[76:79]
	v_mfma_f32_16x16x32_bf16 v[72:75], v[214:217], v[186:189], v[72:75]
	v_mfma_f32_16x16x32_bf16 v[68:71], v[204:207], v[196:199], v[68:71]
	v_mfma_f32_16x16x32_bf16 v[64:67], v[214:217], v[196:199], v[64:67]
	s_setprio 0
	s_mov_b32 m0, s31
	v_lshl_add_u64 v[218:219], v[222:223], 0, s[4:5]
	s_barrier
	ds_read_b128 v[166:169], v148 offset:49152
	ds_read_b128 v[170:173], v148 offset:50176
	ds_read_b128 v[174:177], v148 offset:51200
	ds_read_b128 v[178:181], v148 offset:52224
	ds_read_b128 v[182:185], v148 offset:53248
	ds_read_b128 v[186:189], v148 offset:54272
	ds_read_b128 v[192:195], v148 offset:55296
	ds_read_b128 v[196:199], v148 offset:56320
	global_load_lds_dwordx4 v[218:219], off
	v_lshl_add_u64 v[218:219], v[224:225], 0, s[4:5]
	s_mov_b32 m0, s33
	s_nop 0
	global_load_lds_dwordx4 v[218:219], off
	s_barrier
; #define PG8_STAGE(bufoff, gbase, voff) do { _Pragma("unroll") for (int _i = 0; _i < 2; ++_i) \
;         __builtin_amdgcn_global_load_lds((const unsigned*)((const char*)(gbase) + (voff)[_i]), (LAS unsigned*)(lds + (bufoff) + ldsw + _i * 8192), 16, 0, 0); } while (0)
; #define PG8_LDA(dst, b, h) do { _Pragma("unroll") for (int m = 0; m < 4; ++m) _Pragma("unroll") for (int k = 0; k < 2; ++k) dst[m][k] = *(const LAS bf16x8*)(lds + PG8_SA(b, h) + aoff + m * 2048 + k * 1024); } while (0)
; #define PG8_LDB(dst, b, h) do { _Pragma("unroll") for (int n = 0; n < 2; ++n) _Pragma("unroll") for (int k = 0; k < 2; ++k) dst[n][k] = *(const LAS bf16x8*)(lds + PG8_SB(b, h) + boff + n * 2048 + k * 1024); } while (0)
; #define PG8_MMA(ai, bj, At, Bt) do { __builtin_amdgcn_s_setprio(1); _Pragma("unroll") for (int m = 0; m < 4; ++m) _Pragma("unroll") for (int n = 0; n < 2; ++n) _Pragma("unroll") for (int k = 0; k < 2; ++k) \
;         acc[ai][bj][m][n] = __builtin_amdgcn_mfma_f32_16x16x32_bf16(Bt[n][k], At[m][k], acc[ai][bj][m][n], 0, 0, 0); __builtin_amdgcn_s_setprio(0); } while (0)
; #define PG8_WAIT_V(n) asm volatile("s_waitcnt vmcnt(" #n ")" ::: "memory")
; #define PG8_WAIT_L(n) asm volatile("s_waitcnt lgkmcnt(" #n ")" ::: "memory")
; #define PG8_BAR __builtin_amdgcn_s_barrier()
; #define PG8_SCHED __builtin_amdgcn_sched_barrier(0)
; #define PG8_LDA(dst, b, h) do { _Pragma("unroll") for (int m = 0; m < 4; ++m) _Pragma("unroll") for (int k = 0; k < 2; ++k) dst[m][k] = *(const LAS bf16x8*)(lds + PG8_SA(b, h) + aoff + m * 2048 + k * 1024); } while (0)
; #define PG8_WAIT_V(n) asm volatile("s_waitcnt vmcnt(" #n ")" ::: "memory")
; #define PG8_BAR __builtin_amdgcn_s_barrier()
; template <class Epi, bool AFTER = false>
; __device__ __forceinline__ void gemm_phase(LAS unsigned char* lds, const Gemm g, const StaticOrder& S, const Epi& E) {
;     ...
;             PG8_LDB(B0, 0, 0); PG8_SCHED; PG8_LDA(At, 0, 0); PG8_STAGE(PG8_SA(1, 1), a1 + hstep, voffA);
;             PG8_WAIT_L(8); PG8_BAR; PG8_WAIT_L(0); PG8_MMA(0, 0, At, B0); PG8_BAR; PG8_SCHED;
;             PG8_LDB(B1, 0, 1); PG8_STAGE(PG8_SB(0, 0), b2, voffB);
;             PG8_BAR; PG8_WAIT_L(0); PG8_MMA(0, 1, At, B1); PG8_BAR;
;     ...
;             PG8_BAR; PG8_WAIT_L(0); PG8_MMA(1, 0, At, B0); PG8_BAR; PG8_SCHED;
;             PG8_STAGE(PG8_SB(1, 1), b3 + hstep, voffB);
;             PG8_WAIT_V(6); PG8_BAR; PG8_MMA(1, 1, At, B1); PG8_BAR;
	s_waitcnt lgkmcnt(0)
	s_setprio 1
	s_waitcnt lgkmcnt(0)
	v_mfma_f32_16x16x32_bf16 v[60:63], v[150:153], v[166:169], v[60:63]
	v_mfma_f32_16x16x32_bf16 v[56:59], v[158:161], v[166:169], v[56:59]
	v_mfma_f32_16x16x32_bf16 v[52:55], v[150:153], v[174:177], v[52:55]
	v_mfma_f32_16x16x32_bf16 v[48:51], v[158:161], v[174:177], v[48:51]
	v_mfma_f32_16x16x32_bf16 v[36:39], v[150:153], v[182:185], v[36:39]
	v_mfma_f32_16x16x32_bf16 v[32:35], v[158:161], v[182:185], v[32:35]
	v_mfma_f32_16x16x32_bf16 v[20:23], v[150:153], v[192:195], v[20:23]
	v_mfma_f32_16x16x32_bf16 v[16:19], v[158:161], v[192:195], v[16:19]
	v_mfma_f32_16x16x32_bf16 v[60:63], v[154:157], v[170:173], v[60:63]
	v_mfma_f32_16x16x32_bf16 v[56:59], v[162:165], v[170:173], v[56:59]
	v_mfma_f32_16x16x32_bf16 v[52:55], v[154:157], v[178:181], v[52:55]
	v_mfma_f32_16x16x32_bf16 v[48:51], v[162:165], v[178:181], v[48:51]
	v_mfma_f32_16x16x32_bf16 v[36:39], v[154:157], v[186:189], v[36:39]
	v_mfma_f32_16x16x32_bf16 v[32:35], v[162:165], v[186:189], v[32:35]
	v_mfma_f32_16x16x32_bf16 v[20:23], v[154:157], v[196:199], v[20:23]
	v_mfma_f32_16x16x32_bf16 v[16:19], v[162:165], v[196:199], v[16:19]
	s_setprio 0
	s_barrier
	s_add_u32 s18, s18, 0x40080
	s_addc_u32 s19, s19, 0
	s_add_i32 s20, s20, s23
	v_lshl_add_u64 v[150:151], s[18:19], 0, v[130:131]
	s_mov_b32 m0, s20
	s_nop 0
	global_load_lds_dwordx4 v[150:151], off
	v_lshl_add_u64 v[150:151], s[18:19], 0, v[134:135]
	s_add_i32 m0, s20, 0x2000
	s_nop 0
	global_load_lds_dwordx4 v[150:151], off
	s_waitcnt vmcnt(6)
	s_barrier
	s_setprio 1
	v_mfma_f32_16x16x32_bf16 v[44:47], v[200:203], v[166:169], v[44:47]
	v_mfma_f32_16x16x32_bf16 v[40:43], v[208:211], v[166:169], v[40:43]
	v_mfma_f32_16x16x32_bf16 v[28:31], v[200:203], v[174:177], v[28:31]
	v_mfma_f32_16x16x32_bf16 v[24:27], v[208:211], v[174:177], v[24:27]
	v_mfma_f32_16x16x32_bf16 v[12:15], v[200:203], v[182:185], v[12:15]
	v_mfma_f32_16x16x32_bf16 v[8:11], v[208:211], v[182:185], v[8:11]
	v_mfma_f32_16x16x32_bf16 v[4:7], v[200:203], v[192:195], v[4:7]
	v_mfma_f32_16x16x32_bf16 v[0:3], v[208:211], v[192:195], v[0:3]
	v_mfma_f32_16x16x32_bf16 v[44:47], v[204:207], v[170:173], v[44:47]
	v_mfma_f32_16x16x32_bf16 v[40:43], v[214:217], v[170:173], v[40:43]
	v_mfma_f32_16x16x32_bf16 v[28:31], v[204:207], v[178:181], v[28:31]
	v_mfma_f32_16x16x32_bf16 v[24:27], v[214:217], v[178:181], v[24:27]
	v_mfma_f32_16x16x32_bf16 v[12:15], v[204:207], v[186:189], v[12:15]
	v_mfma_f32_16x16x32_bf16 v[8:11], v[214:217], v[186:189], v[8:11]
	v_mfma_f32_16x16x32_bf16 v[4:7], v[204:207], v[196:199], v[4:7]
	v_mfma_f32_16x16x32_bf16 v[0:3], v[214:217], v[196:199], v[0:3]
	s_setprio 0
	s_add_i32 s43, s43, 2
	s_add_u32 s16, s16, 0x100
	s_addc_u32 s17, s17, 0
	s_add_u32 s41, s41, 0x100
	s_addc_u32 s42, s42, 0
	s_cmp_gt_u32 s43, 13
	s_barrier
.LBB0_118:
	ds_read_b128 v[150:153], v147
	ds_read_b128 v[154:157], v147 offset:1024
	ds_read_b128 v[158:161], v147 offset:2048
	ds_read_b128 v[162:165], v147 offset:3072
	s_add_u32 s18, s16, 0xfffc0080
	s_addc_u32 s19, s17, -1
	s_cmp_eq_u32 s43, 12
	s_cselect_b32 s21, s11, s19
	s_cselect_b32 s20, s39, s18
	s_cselect_b32 s19, s9, s42
	s_cselect_b32 s18, s40, s41
	v_lshl_add_u64 v[200:201], s[16:17], 0, v[136:137]
	s_add_i32 m0, s7, 0xc000
	ds_read_b128 v[166:169], v148
	ds_read_b128 v[170:173], v148 offset:1024
	ds_read_b128 v[174:177], v148 offset:2048
	ds_read_b128 v[178:181], v148 offset:3072
	ds_read_b128 v[182:185], v148 offset:4096
	ds_read_b128 v[186:189], v148 offset:5120
	ds_read_b128 v[192:195], v148 offset:6144
	ds_read_b128 v[196:199], v148 offset:7168
	global_load_lds_dwordx4 v[200:201], off
	v_lshl_add_u64 v[200:201], s[16:17], 0, v[138:139]
	s_add_i32 m0, s7, 0xe000
	s_nop 0
	global_load_lds_dwordx4 v[200:201], off
	s_waitcnt lgkmcnt(8)
	s_barrier
	s_waitcnt lgkmcnt(0)
	s_setprio 1
	s_waitcnt lgkmcnt(0)
	v_mfma_f32_16x16x32_bf16 v[124:127], v[150:153], v[166:169], v[124:127]
	v_mfma_f32_16x16x32_bf16 v[120:123], v[158:161], v[166:169], v[120:123]
	v_mfma_f32_16x16x32_bf16 v[116:119], v[150:153], v[174:177], v[116:119]
	v_mfma_f32_16x16x32_bf16 v[112:115], v[158:161], v[174:177], v[112:115]
	v_mfma_f32_16x16x32_bf16 v[100:103], v[150:153], v[182:185], v[100:103]
	v_mfma_f32_16x16x32_bf16 v[96:99], v[158:161], v[182:185], v[96:99]
	v_mfma_f32_16x16x32_bf16 v[84:87], v[150:153], v[192:195], v[84:87]
	v_mfma_f32_16x16x32_bf16 v[80:83], v[158:161], v[192:195], v[80:83]
	v_mfma_f32_16x16x32_bf16 v[124:127], v[154:157], v[170:173], v[124:127]
	v_mfma_f32_16x16x32_bf16 v[120:123], v[162:165], v[170:173], v[120:123]
	v_mfma_f32_16x16x32_bf16 v[116:119], v[154:157], v[178:181], v[116:119]
	v_mfma_f32_16x16x32_bf16 v[112:115], v[162:165], v[178:181], v[112:115]
	v_mfma_f32_16x16x32_bf16 v[100:103], v[154:157], v[186:189], v[100:103]
	v_mfma_f32_16x16x32_bf16 v[96:99], v[162:165], v[186:189], v[96:99]
	v_mfma_f32_16x16x32_bf16 v[84:87], v[154:157], v[196:199], v[84:87]
	v_mfma_f32_16x16x32_bf16 v[80:83], v[162:165], v[196:199], v[80:83]
	s_setprio 0
	s_barrier
	s_add_i32 s44, s35, s23
	v_lshl_add_u64 v[218:219], s[18:19], 0, v[130:131]
	s_mov_b32 m0, s44
	ds_read_b128 v[200:203], v149
	ds_read_b128 v[204:207], v149 offset:1024
	ds_read_b128 v[208:211], v149 offset:2048
	ds_read_b128 v[214:217], v149 offset:3072
	global_load_lds_dwordx4 v[218:219], off
	v_lshl_add_u64 v[220:221], s[18:19], 0, v[134:135]
	s_add_i32 m0, s44, 0x2000
	s_nop 0
	global_load_lds_dwordx4 v[220:221], off
	s_barrier
; #define PG8_STAGE(bufoff, gbase, voff) do { _Pragma("unroll") for (int _i = 0; _i < 2; ++_i) \
;         __builtin_amdgcn_global_load_lds((const unsigned*)((const char*)(gbase) + (voff)[_i]), (LAS unsigned*)(lds + (bufoff) + ldsw + _i * 8192), 16, 0, 0); } while (0)
; #define PG8_LDA(dst, b, h) do { _Pragma("unroll") for (int m = 0; m < 4; ++m) _Pragma("unroll") for (int k = 0; k < 2; ++k) dst[m][k] = *(const LAS bf16x8*)(lds + PG8_SA(b, h) + aoff + m * 2048 + k * 1024); } while (0)
; #define PG8_LDB(dst, b, h) do { _Pragma("unroll") for (int n = 0; n < 2; ++n) _Pragma("unroll") for (int k = 0; k < 2; ++k) dst[n][k] = *(const LAS bf16x8*)(lds + PG8_SB(b, h) + boff + n * 2048 + k * 1024); } while (0)
; #define PG8_MMA(ai, bj, At, Bt) do { __builtin_amdgcn_s_setprio(1); _Pragma("unroll") for (int m = 0; m < 4; ++m) _Pragma("unroll") for (int n = 0; n < 2; ++n) _Pragma("unroll") for (int k = 0; k < 2; ++k) \
;         acc[ai][bj][m][n] = __builtin_amdgcn_mfma_f32_16x16x32_bf16(Bt[n][k], At[m][k], acc[ai][bj][m][n], 0, 0, 0); __builtin_amdgcn_s_setprio(0); } while (0)
; #define PG8_WAIT_V(n) asm volatile("s_waitcnt vmcnt(" #n ")" ::: "memory")
; #define PG8_WAIT_L(n) asm volatile("s_waitcnt lgkmcnt(" #n ")" ::: "memory")
; #define PG8_BAR __builtin_amdgcn_s_barrier()
; #define PG8_SCHED __builtin_amdgcn_sched_barrier(0)
; #define PG8_LDA(dst, b, h) do { _Pragma("unroll") for (int m = 0; m < 4; ++m) _Pragma("unroll") for (int k = 0; k < 2; ++k) dst[m][k] = *(const LAS bf16x8*)(lds + PG8_SA(b, h) + aoff + m * 2048 + k * 1024); } while (0)
; #define PG8_WAIT_V(n) asm volatile("s_waitcnt vmcnt(" #n ")" ::: "memory")
; #define PG8_BAR __builtin_amdgcn_s_barrier()
; template <class Epi, bool AFTER = false>
; __device__ __forceinline__ void gemm_phase(LAS unsigned char* lds, const Gemm g, const StaticOrder& S, const Epi& E) {
;     ...
;             PG8_BAR; PG8_WAIT_L(0); PG8_MMA(0, 1, At, B1); PG8_BAR;
;             PG8_LDA(At, 0, 1); PG8_STAGE(PG8_SA(0, 0), a2, voffA);
;             PG8_BAR; PG8_WAIT_L(0); PG8_MMA(1, 0, At, B0); PG8_BAR; PG8_SCHED;
;             PG8_STAGE(PG8_SB(0, 1), b2 + hstep, voffB);
;             PG8_WAIT_V(6); PG8_BAR; PG8_MMA(1, 1, At, B1); PG8_BAR;
;             PG8_LDB(B0, 1, 0); PG8_SCHED; PG8_LDA(At, 1, 0); PG8_STAGE(PG8_SA(0, 1), a2 + hstep, voffA);
;             PG8_WAIT_L(8); PG8_BAR; PG8_WAIT_L(0); PG8_MMA(0, 0, At, B0); PG8_BAR; PG8_SCHED;
	s_waitcnt lgkmcnt(0)
	s_setprio 1
	s_waitcnt lgkmcnt(0)
	v_mfma_f32_16x16x32_bf16 v[108:111], v[200:203], v[166:169], v[108:111]
	v_mfma_f32_16x16x32_bf16 v[104:107], v[208:211], v[166:169], v[104:107]
	v_mfma_f32_16x16x32_bf16 v[92:95], v[200:203], v[174:177], v[92:95]
	v_mfma_f32_16x16x32_bf16 v[88:91], v[208:211], v[174:177], v[88:91]
	v_mfma_f32_16x16x32_bf16 v[76:79], v[200:203], v[182:185], v[76:79]
	v_mfma_f32_16x16x32_bf16 v[72:75], v[208:211], v[182:185], v[72:75]
	v_mfma_f32_16x16x32_bf16 v[68:71], v[200:203], v[192:195], v[68:71]
	v_mfma_f32_16x16x32_bf16 v[64:67], v[208:211], v[192:195], v[64:67]
	v_mfma_f32_16x16x32_bf16 v[108:111], v[204:207], v[170:173], v[108:111]
	v_mfma_f32_16x16x32_bf16 v[104:107], v[214:217], v[170:173], v[104:107]
	v_mfma_f32_16x16x32_bf16 v[92:95], v[204:207], v[178:181], v[92:95]
	v_mfma_f32_16x16x32_bf16 v[88:91], v[214:217], v[178:181], v[88:91]
	v_mfma_f32_16x16x32_bf16 v[76:79], v[204:207], v[186:189], v[76:79]
	v_mfma_f32_16x16x32_bf16 v[72:75], v[214:217], v[186:189], v[72:75]
	v_mfma_f32_16x16x32_bf16 v[68:71], v[204:207], v[196:199], v[68:71]
	v_mfma_f32_16x16x32_bf16 v[64:67], v[214:217], v[196:199], v[64:67]
	s_setprio 0
	s_mov_b32 m0, s7
	v_lshl_add_u64 v[222:223], s[20:21], 0, v[128:129]
	s_barrier
	ds_read_b128 v[166:169], v148 offset:16384
	ds_read_b128 v[170:173], v148 offset:17408
	ds_read_b128 v[174:177], v148 offset:18432
	ds_read_b128 v[178:181], v148 offset:19456
	ds_read_b128 v[182:185], v148 offset:20480
	ds_read_b128 v[186:189], v148 offset:21504
	ds_read_b128 v[192:195], v148 offset:22528
	ds_read_b128 v[196:199], v148 offset:23552
	global_load_lds_dwordx4 v[222:223], off
	v_lshl_add_u64 v[224:225], s[20:21], 0, v[132:133]
	s_mov_b32 m0, s26
	s_nop 0
	global_load_lds_dwordx4 v[224:225], off
	s_barrier
	s_waitcnt lgkmcnt(0)
	s_setprio 1
	s_waitcnt lgkmcnt(0)
	v_mfma_f32_16x16x32_bf16 v[60:63], v[150:153], v[166:169], v[60:63]
	v_mfma_f32_16x16x32_bf16 v[56:59], v[158:161], v[166:169], v[56:59]
	v_mfma_f32_16x16x32_bf16 v[52:55], v[150:153], v[174:177], v[52:55]
	v_mfma_f32_16x16x32_bf16 v[48:51], v[158:161], v[174:177], v[48:51]
	v_mfma_f32_16x16x32_bf16 v[36:39], v[150:153], v[182:185], v[36:39]
	v_mfma_f32_16x16x32_bf16 v[32:35], v[158:161], v[182:185], v[32:35]
	v_mfma_f32_16x16x32_bf16 v[20:23], v[150:153], v[192:195], v[20:23]
	v_mfma_f32_16x16x32_bf16 v[16:19], v[158:161], v[192:195], v[16:19]
	v_mfma_f32_16x16x32_bf16 v[60:63], v[154:157], v[170:173], v[60:63]
	v_mfma_f32_16x16x32_bf16 v[56:59], v[162:165], v[170:173], v[56:59]
	v_mfma_f32_16x16x32_bf16 v[52:55], v[154:157], v[178:181], v[52:55]
	v_mfma_f32_16x16x32_bf16 v[48:51], v[162:165], v[178:181], v[48:51]
	v_mfma_f32_16x16x32_bf16 v[36:39], v[154:157], v[186:189], v[36:39]
	v_mfma_f32_16x16x32_bf16 v[32:35], v[162:165], v[186:189], v[32:35]
	v_mfma_f32_16x16x32_bf16 v[20:23], v[154:157], v[196:199], v[20:23]
	v_mfma_f32_16x16x32_bf16 v[16:19], v[162:165], v[196:199], v[16:19]
	s_setprio 0
	s_barrier
	s_add_u32 s44, s18, 0x40000
	s_addc_u32 s45, s19, 0
	s_add_i32 s46, s36, s23
	v_lshl_add_u64 v[150:151], s[44:45], 0, v[130:131]
	s_mov_b32 m0, s46
	s_nop 0
	global_load_lds_dwordx4 v[150:151], off
	v_lshl_add_u64 v[150:151], s[44:45], 0, v[134:135]
	s_add_i32 m0, s46, 0x2000
	s_nop 0
	global_load_lds_dwordx4 v[150:151], off
	s_waitcnt vmcnt(6)
	s_barrier
	s_setprio 1
	v_mfma_f32_16x16x32_bf16 v[44:47], v[200:203], v[166:169], v[44:47]
	v_mfma_f32_16x16x32_bf16 v[40:43], v[208:211], v[166:169], v[40:43]
	v_mfma_f32_16x16x32_bf16 v[28:31], v[200:203], v[174:177], v[28:31]
	v_mfma_f32_16x16x32_bf16 v[24:27], v[208:211], v[174:177], v[24:27]
	v_mfma_f32_16x16x32_bf16 v[12:15], v[200:203], v[182:185], v[12:15]
	v_mfma_f32_16x16x32_bf16 v[8:11], v[208:211], v[182:185], v[8:11]
	v_mfma_f32_16x16x32_bf16 v[4:7], v[200:203], v[192:195], v[4:7]
	v_mfma_f32_16x16x32_bf16 v[0:3], v[208:211], v[192:195], v[0:3]
	v_mfma_f32_16x16x32_bf16 v[44:47], v[204:207], v[170:173], v[44:47]
	v_mfma_f32_16x16x32_bf16 v[40:43], v[214:217], v[170:173], v[40:43]
	v_mfma_f32_16x16x32_bf16 v[28:31], v[204:207], v[178:181], v[28:31]
	v_mfma_f32_16x16x32_bf16 v[24:27], v[214:217], v[178:181], v[24:27]
	v_mfma_f32_16x16x32_bf16 v[12:15], v[204:207], v[186:189], v[12:15]
	v_mfma_f32_16x16x32_bf16 v[8:11], v[214:217], v[186:189], v[8:11]
	v_mfma_f32_16x16x32_bf16 v[4:7], v[204:207], v[196:199], v[4:7]
	v_mfma_f32_16x16x32_bf16 v[0:3], v[214:217], v[196:199], v[0:3]
	s_setprio 0
	s_add_i32 s44, 0, 0x18000
	v_add_u32_e32 v162, s44, v145
	s_barrier
	ds_read_b128 v[150:153], v162
	ds_read_b128 v[154:157], v162 offset:1024
	ds_read_b128 v[158:161], v162 offset:2048
	ds_read_b128 v[162:165], v162 offset:3072
	s_add_u32 s20, s20, 0x40000
	s_addc_u32 s21, s21, 0
	s_mov_b32 m0, s27
	v_lshl_add_u64 v[200:201], s[20:21], 0, v[128:129]
	ds_read_b128 v[166:169], v148 offset:32768
	ds_read_b128 v[170:173], v148 offset:33792
	ds_read_b128 v[174:177], v148 offset:34816
	ds_read_b128 v[178:181], v148 offset:35840
	ds_read_b128 v[182:185], v148 offset:36864
	ds_read_b128 v[186:189], v148 offset:37888
	ds_read_b128 v[192:195], v148 offset:38912
	ds_read_b128 v[196:199], v148 offset:39936
	global_load_lds_dwordx4 v[200:201], off
	v_lshl_add_u64 v[200:201], s[20:21], 0, v[132:133]
	s_mov_b32 m0, s28
	s_nop 0
	global_load_lds_dwordx4 v[200:201], off
	s_waitcnt lgkmcnt(8)
	s_barrier
; #define PG8_STAGE(bufoff, gbase, voff) do { _Pragma("unroll") for (int _i = 0; _i < 2; ++_i) \
;         __builtin_amdgcn_global_load_lds((const unsigned*)((const char*)(gbase) + (voff)[_i]), (LAS unsigned*)(lds + (bufoff) + ldsw + _i * 8192), 16, 0, 0); } while (0)
; #define PG8_LDA(dst, b, h) do { _Pragma("unroll") for (int m = 0; m < 4; ++m) _Pragma("unroll") for (int k = 0; k < 2; ++k) dst[m][k] = *(const LAS bf16x8*)(lds + PG8_SA(b, h) + aoff + m * 2048 + k * 1024); } while (0)
; #define PG8_LDB(dst, b, h) do { _Pragma("unroll") for (int n = 0; n < 2; ++n) _Pragma("unroll") for (int k = 0; k < 2; ++k) dst[n][k] = *(const LAS bf16x8*)(lds + PG8_SB(b, h) + boff + n * 2048 + k * 1024); } while (0)
; #define PG8_MMA(ai, bj, At, Bt) do { __builtin_amdgcn_s_setprio(1); _Pragma("unroll") for (int m = 0; m < 4; ++m) _Pragma("unroll") for (int n = 0; n < 2; ++n) _Pragma("unroll") for (int k = 0; k < 2; ++k) \
;         acc[ai][bj][m][n] = __builtin_amdgcn_mfma_f32_16x16x32_bf16(Bt[n][k], At[m][k], acc[ai][bj][m][n], 0, 0, 0); __builtin_amdgcn_s_setprio(0); } while (0)
; #define PG8_WAIT_V(n) asm volatile("s_waitcnt vmcnt(" #n ")" ::: "memory")
; #define PG8_WAIT_L(n) asm volatile("s_waitcnt lgkmcnt(" #n ")" ::: "memory")
; #define PG8_BAR __builtin_amdgcn_s_barrier()
; #define PG8_SCHED __builtin_amdgcn_sched_barrier(0)
; #define PG8_LDA(dst, b, h) do { _Pragma("unroll") for (int m = 0; m < 4; ++m) _Pragma("unroll") for (int k = 0; k < 2; ++k) dst[m][k] = *(const LAS bf16x8*)(lds + PG8_SA(b, h) + aoff + m * 2048 + k * 1024); } while (0)
; #define PG8_WAIT_V(n) asm volatile("s_waitcnt vmcnt(" #n ")" ::: "memory")
; #define PG8_WAIT_L(n) asm volatile("s_waitcnt lgkmcnt(" #n ")" ::: "memory")
; template <class Epi, bool AFTER = false>
; __device__ __forceinline__ void gemm_phase(LAS unsigned char* lds, const Gemm g, const StaticOrder& S, const Epi& E) {
;     ...
;             PG8_WAIT_L(8); PG8_BAR; PG8_WAIT_L(0); PG8_MMA(0, 0, At, B0); PG8_BAR; PG8_SCHED;
;             PG8_LDB(B1, 1, 1); PG8_STAGE(PG8_SB(1, 0), b3, voffB);
;             PG8_BAR; PG8_WAIT_L(0); PG8_MMA(0, 1, At, B1); PG8_BAR;
;             PG8_LDA(At, 1, 1); PG8_STAGE(PG8_SA(1, 0), a3, voffA);
;             PG8_BAR; PG8_WAIT_L(0); PG8_MMA(1, 0, At, B0); PG8_BAR; PG8_SCHED;
;             PG8_STAGE(PG8_SB(1, 1), b3 + hstep, voffB);
;             PG8_WAIT_V(6); PG8_BAR; PG8_MMA(1, 1, At, B1); PG8_BAR;
	s_waitcnt lgkmcnt(0)
	s_setprio 1
	s_waitcnt lgkmcnt(0)
	v_mfma_f32_16x16x32_bf16 v[124:127], v[150:153], v[166:169], v[124:127]
	v_mfma_f32_16x16x32_bf16 v[120:123], v[158:161], v[166:169], v[120:123]
	v_mfma_f32_16x16x32_bf16 v[116:119], v[150:153], v[174:177], v[116:119]
	v_mfma_f32_16x16x32_bf16 v[112:115], v[158:161], v[174:177], v[112:115]
	v_mfma_f32_16x16x32_bf16 v[100:103], v[150:153], v[182:185], v[100:103]
	v_mfma_f32_16x16x32_bf16 v[96:99], v[158:161], v[182:185], v[96:99]
	v_mfma_f32_16x16x32_bf16 v[84:87], v[150:153], v[192:195], v[84:87]
	v_mfma_f32_16x16x32_bf16 v[80:83], v[158:161], v[192:195], v[80:83]
	v_mfma_f32_16x16x32_bf16 v[124:127], v[154:157], v[170:173], v[124:127]
	v_mfma_f32_16x16x32_bf16 v[120:123], v[162:165], v[170:173], v[120:123]
	v_mfma_f32_16x16x32_bf16 v[116:119], v[154:157], v[178:181], v[116:119]
	v_mfma_f32_16x16x32_bf16 v[112:115], v[162:165], v[178:181], v[112:115]
	v_mfma_f32_16x16x32_bf16 v[100:103], v[154:157], v[186:189], v[100:103]
	v_mfma_f32_16x16x32_bf16 v[96:99], v[162:165], v[186:189], v[96:99]
	v_mfma_f32_16x16x32_bf16 v[84:87], v[154:157], v[196:199], v[84:87]
	v_mfma_f32_16x16x32_bf16 v[80:83], v[162:165], v[196:199], v[80:83]
	s_setprio 0
	s_barrier
	s_add_i32 s20, 0, 0x1c000
	s_add_i32 s21, s44, s23
	v_add_u32_e32 v191, s20, v145
	v_lshl_add_u64 v[218:219], v[218:219], 0, s[4:5]
	s_mov_b32 m0, s21
	ds_read_b128 v[200:203], v191
	ds_read_b128 v[204:207], v191 offset:1024
	ds_read_b128 v[208:211], v191 offset:2048
	ds_read_b128 v[214:217], v191 offset:3072
	global_load_lds_dwordx4 v[218:219], off
	v_lshl_add_u64 v[218:219], v[220:221], 0, s[4:5]
	s_add_i32 m0, s21, 0x2000
	s_nop 0
	global_load_lds_dwordx4 v[218:219], off
	s_barrier
	s_waitcnt lgkmcnt(0)
	s_setprio 1
	s_waitcnt lgkmcnt(0)
	v_mfma_f32_16x16x32_bf16 v[108:111], v[200:203], v[166:169], v[108:111]
	v_mfma_f32_16x16x32_bf16 v[104:107], v[208:211], v[166:169], v[104:107]
	v_mfma_f32_16x16x32_bf16 v[92:95], v[200:203], v[174:177], v[92:95]
	v_mfma_f32_16x16x32_bf16 v[88:91], v[208:211], v[174:177], v[88:91]
	v_mfma_f32_16x16x32_bf16 v[76:79], v[200:203], v[182:185], v[76:79]
	v_mfma_f32_16x16x32_bf16 v[72:75], v[208:211], v[182:185], v[72:75]
	v_mfma_f32_16x16x32_bf16 v[68:71], v[200:203], v[192:195], v[68:71]
	v_mfma_f32_16x16x32_bf16 v[64:67], v[208:211], v[192:195], v[64:67]
	v_mfma_f32_16x16x32_bf16 v[108:111], v[204:207], v[170:173], v[108:111]
	v_mfma_f32_16x16x32_bf16 v[104:107], v[214:217], v[170:173], v[104:107]
	v_mfma_f32_16x16x32_bf16 v[92:95], v[204:207], v[178:181], v[92:95]
	v_mfma_f32_16x16x32_bf16 v[88:91], v[214:217], v[178:181], v[88:91]
	v_mfma_f32_16x16x32_bf16 v[76:79], v[204:207], v[186:189], v[76:79]
	v_mfma_f32_16x16x32_bf16 v[72:75], v[214:217], v[186:189], v[72:75]
	v_mfma_f32_16x16x32_bf16 v[68:71], v[204:207], v[196:199], v[68:71]
	v_mfma_f32_16x16x32_bf16 v[64:67], v[214:217], v[196:199], v[64:67]
	s_setprio 0
	s_mov_b32 m0, s31
	v_lshl_add_u64 v[218:219], v[222:223], 0, s[4:5]
	s_barrier
	ds_read_b128 v[166:169], v148 offset:49152
	ds_read_b128 v[170:173], v148 offset:50176
	ds_read_b128 v[174:177], v148 offset:51200
	ds_read_b128 v[178:181], v148 offset:52224
	ds_read_b128 v[182:185], v148 offset:53248
	ds_read_b128 v[186:189], v148 offset:54272
	ds_read_b128 v[192:195], v148 offset:55296
	ds_read_b128 v[196:199], v148 offset:56320
	global_load_lds_dwordx4 v[218:219], off
	v_lshl_add_u64 v[218:219], v[224:225], 0, s[4:5]
	s_mov_b32 m0, s33
	s_nop 0
	global_load_lds_dwordx4 v[218:219], off
	s_barrier
	s_waitcnt lgkmcnt(0)
	s_setprio 1
	s_waitcnt lgkmcnt(0)
	v_mfma_f32_16x16x32_bf16 v[60:63], v[150:153], v[166:169], v[60:63]
	v_mfma_f32_16x16x32_bf16 v[56:59], v[158:161], v[166:169], v[56:59]
	v_mfma_f32_16x16x32_bf16 v[52:55], v[150:153], v[174:177], v[52:55]
	v_mfma_f32_16x16x32_bf16 v[48:51], v[158:161], v[174:177], v[48:51]
	v_mfma_f32_16x16x32_bf16 v[36:39], v[150:153], v[182:185], v[36:39]
	v_mfma_f32_16x16x32_bf16 v[32:35], v[158:161], v[182:185], v[32:35]
	v_mfma_f32_16x16x32_bf16 v[20:23], v[150:153], v[192:195], v[20:23]
	v_mfma_f32_16x16x32_bf16 v[16:19], v[158:161], v[192:195], v[16:19]
	v_mfma_f32_16x16x32_bf16 v[60:63], v[154:157], v[170:173], v[60:63]
	v_mfma_f32_16x16x32_bf16 v[56:59], v[162:165], v[170:173], v[56:59]
	v_mfma_f32_16x16x32_bf16 v[52:55], v[154:157], v[178:181], v[52:55]
	v_mfma_f32_16x16x32_bf16 v[48:51], v[162:165], v[178:181], v[48:51]
	v_mfma_f32_16x16x32_bf16 v[36:39], v[154:157], v[186:189], v[36:39]
	v_mfma_f32_16x16x32_bf16 v[32:35], v[162:165], v[186:189], v[32:35]
	v_mfma_f32_16x16x32_bf16 v[20:23], v[154:157], v[196:199], v[20:23]
	v_mfma_f32_16x16x32_bf16 v[16:19], v[162:165], v[196:199], v[16:19]
	s_setprio 0
	s_barrier
	s_add_u32 s18, s18, 0x40080
	s_addc_u32 s19, s19, 0
	s_add_i32 s20, s20, s23
	v_lshl_add_u64 v[150:151], s[18:19], 0, v[130:131]
	s_mov_b32 m0, s20
	s_nop 0
	global_load_lds_dwordx4 v[150:151], off
	v_lshl_add_u64 v[150:151], s[18:19], 0, v[134:135]
	s_add_i32 m0, s20, 0x2000
	s_nop 0
	global_load_lds_dwordx4 v[150:151], off
	s_waitcnt vmcnt(6)
	s_barrier
; __device__ __forceinline__ unsigned cvt_pk_bf16(float lo, float hi) { const f32x2_t f = {lo, hi}; const bf16x2_t b = __builtin_convertvector(f, bf16x2_t); return __builtin_bit_cast(unsigned, b); }
; __device__ __forceinline__ void st_wt16(void* p, u32x4 v) { asm volatile("global_store_dwordx4 %0, %1, off sc1\n\ts_nop 1" : : "v"(p), "v"(v) : "memory"); }
; #define PG8_WAIT_V(n) asm volatile("s_waitcnt vmcnt(" #n ")" ::: "memory")
; template <class Epi, bool AFTER = false>
; __device__ __forceinline__ void gemm_phase(LAS unsigned char* lds, const Gemm g, const StaticOrder& S, const Epi& E) {
;     ...
;             PG8_WAIT_V(6); PG8_BAR; PG8_MMA(1, 1, At, B1); PG8_BAR;
;         }
;         if constexpr (!AFTER) E(acc, cur, wr, wc, fr, fq);
;         if (!has_next) break;
; #pragma unroll
;         for (int a = 0; a < 2; ++a)
; #pragma unroll
;             for (int b = 0; b < 2; ++b)
; #pragma unroll
;                 for (int m = 0; m < 4; ++m)
; #pragma unroll
;                     for (int n = 0; n < 2; ++n) acc[a][b][m][n] = (f32x4){0.f, 0.f, 0.f, 0.f};
;         cur = nxt; cA = nA; cB = nB; ++ui;
;     __device__ __forceinline__ void operator()(const f32x4 (&acc)[2][2][4][2], const pg8::Unit& u, int wr, int wc, int fr, int fq) const {
;         bf16_t* base; int ld, colt;
;         if (u.pn < split_pn) { base = O1; ld = ld1; colt = u.pn * 256; } else { base = O2; ld = ld2; colt = (u.pn - split_pn) * 256; }
;         const int col0 = colt + wc * 32 + 8 * fq; const int row0 = u.pm * 256 + wr * 64 + fr;
; #pragma unroll
;         for (int ai = 0; ai < 2; ++ai)
; #pragma unroll
;             for (int m = 0; m < 4; ++m) {
;                 bf16_t* rp = base + (size_t)(row0 + ai * 128 + m * 16) * ld + col0;
;                 u32x4 w0, w1;
;                 w0.x = cvt_pk_bf16(acc[ai][0][m][0][0], acc[ai][0][m][0][1]); w0.y = cvt_pk_bf16(acc[ai][0][m][0][2], acc[ai][0][m][0][3]);
;                 w0.z = cvt_pk_bf16(acc[ai][0][m][1][0], acc[ai][0][m][1][1]); w0.w = cvt_pk_bf16(acc[ai][0][m][1][2], acc[ai][0][m][1][3]);
;                 w1.x = cvt_pk_bf16(acc[ai][1][m][0][0], acc[ai][1][m][0][1]); w1.y = cvt_pk_bf16(acc[ai][1][m][0][2], acc[ai][1][m][0][3]);
;                 w1.z = cvt_pk_bf16(acc[ai][1][m][1][0], acc[ai][1][m][1][1]); w1.w = cvt_pk_bf16(acc[ai][1][m][1][2], acc[ai][1][m][1][3]);
;                 st_wt16(rp, w0); st_wt16_o256(rp, w1);
	s_setprio 1
	v_mfma_f32_16x16x32_bf16 v[44:47], v[200:203], v[166:169], v[44:47]
	v_mfma_f32_16x16x32_bf16 v[40:43], v[208:211], v[166:169], v[40:43]
	v_mfma_f32_16x16x32_bf16 v[28:31], v[200:203], v[174:177], v[28:31]
	v_mfma_f32_16x16x32_bf16 v[24:27], v[208:211], v[174:177], v[24:27]
	v_mfma_f32_16x16x32_bf16 v[12:15], v[200:203], v[182:185], v[12:15]
	v_mfma_f32_16x16x32_bf16 v[8:11], v[208:211], v[182:185], v[8:11]
	v_mfma_f32_16x16x32_bf16 v[4:7], v[200:203], v[192:195], v[4:7]
	v_mfma_f32_16x16x32_bf16 v[0:3], v[208:211], v[192:195], v[0:3]
	v_mfma_f32_16x16x32_bf16 v[44:47], v[204:207], v[170:173], v[44:47]
	v_mfma_f32_16x16x32_bf16 v[40:43], v[214:217], v[170:173], v[40:43]
	v_mfma_f32_16x16x32_bf16 v[28:31], v[204:207], v[178:181], v[28:31]
	v_mfma_f32_16x16x32_bf16 v[24:27], v[214:217], v[178:181], v[24:27]
	v_mfma_f32_16x16x32_bf16 v[12:15], v[204:207], v[186:189], v[12:15]
	v_mfma_f32_16x16x32_bf16 v[8:11], v[214:217], v[186:189], v[8:11]
	v_mfma_f32_16x16x32_bf16 v[4:7], v[204:207], v[196:199], v[4:7]
	v_mfma_f32_16x16x32_bf16 v[0:3], v[214:217], v[196:199], v[0:3]
	s_setprio 0
	s_add_i32 s43, s43, 2
	s_add_u32 s16, s16, 0x100
	s_addc_u32 s17, s17, 0
	s_add_u32 s41, s41, 0x100
	s_addc_u32 s42, s42, 0
	s_cmp_gt_u32 s43, 13
	s_barrier
	s_cbranch_scc0 .LBB0_118
	s_and_b64 vcc, exec, s[2:3]
	s_cbranch_vccnz .Lg1_fullepi
	v_lshl_or_b32 v226, s38, 8, v146
	v_readlane_b32 s16, v254, 20
	v_ashrrev_i32_e32 v227, 31, v226
	v_readlane_b32 s17, v254, 21
	v_lshl_add_u32 v228, s6, 8, v144
	s_nop 1
	v_lshl_add_u64 v[226:227], v[226:227], 1, s[16:17]
	v_mad_i64_i32 v[230:231], s[98:99], v228, s37, v[226:227]
	v_cvt_pk_bf16_f32 v124, v124, v125
	v_cvt_pk_bf16_f32 v125, v126, v127
	v_cvt_pk_bf16_f32 v126, v120, v121
	v_cvt_pk_bf16_f32 v127, v122, v123
	global_store_dwordx4 v[230:231], v[124:127], off sc1
	s_nop 1
	v_or_b32_e32 v229, 16, v228
	v_mad_i64_i32 v[232:233], s[98:99], v229, s37, v[226:227]
	v_cvt_pk_bf16_f32 v116, v116, v117
	v_cvt_pk_bf16_f32 v117, v118, v119
	v_cvt_pk_bf16_f32 v118, v112, v113
	v_cvt_pk_bf16_f32 v119, v114, v115
	global_store_dwordx4 v[232:233], v[116:119], off sc1
	s_nop 1
	v_or_b32_e32 v229, 32, v228
	v_mad_i64_i32 v[234:235], s[98:99], v229, s37, v[226:227]
	v_cvt_pk_bf16_f32 v100, v100, v101
	v_cvt_pk_bf16_f32 v101, v102, v103
	v_cvt_pk_bf16_f32 v102, v96, v97
	v_cvt_pk_bf16_f32 v103, v98, v99
	global_store_dwordx4 v[234:235], v[100:103], off sc1
	s_nop 1
	v_or_b32_e32 v229, 48, v228
	v_mad_i64_i32 v[236:237], s[98:99], v229, s37, v[226:227]
	v_cvt_pk_bf16_f32 v84, v84, v85
	v_cvt_pk_bf16_f32 v85, v86, v87
	v_cvt_pk_bf16_f32 v86, v80, v81
	v_cvt_pk_bf16_f32 v87, v82, v83
	global_store_dwordx4 v[236:237], v[84:87], off sc1
	s_nop 1
	s_mov_b32 s100, 1
	s_mov_b32 s38, s8
	s_mov_b32 s6, s10
	s_mov_b64 s[18:19], s[14:15]
	s_mov_b64 s[16:17], s[12:13]
	s_branch .LBB0_115
; __device__ __forceinline__ unsigned cvt_pk_bf16(float lo, float hi) { const f32x2_t f = {lo, hi}; const bf16x2_t b = __builtin_convertvector(f, bf16x2_t); return __builtin_bit_cast(unsigned, b); }
; __device__ __forceinline__ void st_wt16(void* p, u32x4 v) { asm volatile("global_store_dwordx4 %0, %1, off sc1\n\ts_nop 1" : : "v"(p), "v"(v) : "memory"); }
; __device__ __forceinline__ void st_wt16_o256(void* p, u32x4 v) { asm volatile("global_store_dwordx4 %0, %1, off offset:256 sc1\n\ts_nop 1" : : "v"(p), "v"(v) : "memory"); }
; #define PG8_WAIT_V(n) asm volatile("s_waitcnt vmcnt(" #n ")" ::: "memory")
; #define PG8_BAR __builtin_amdgcn_s_barrier()
; #define PG8_WAIT_V(n) asm volatile("s_waitcnt vmcnt(" #n ")" ::: "memory")
; #define PG8_BAR __builtin_amdgcn_s_barrier()
; template <class Epi, bool AFTER = false>
; __device__ __forceinline__ void gemm_phase(LAS unsigned char* lds, const Gemm g, const StaticOrder& S, const Epi& E) {
;     ...
;         cur = nxt; cA = nA; cB = nB; ++ui;
;     }
;     PG8_WAIT_V(0);
;     if (wr == 0) PG8_BAR;
;     PG8_BAR;
;     __device__ __forceinline__ void operator()(const f32x4 (&acc)[2][2][4][2], const pg8::Unit& u, int wr, int wc, int fr, int fq) const {
;         bf16_t* base; int ld, colt;
;         if (u.pn < split_pn) { base = O1; ld = ld1; colt = u.pn * 256; } else { base = O2; ld = ld2; colt = (u.pn - split_pn) * 256; }
;         const int col0 = colt + wc * 32 + 8 * fq; const int row0 = u.pm * 256 + wr * 64 + fr;
; #pragma unroll
;         for (int ai = 0; ai < 2; ++ai)
; #pragma unroll
;             for (int m = 0; m < 4; ++m) {
;                 bf16_t* rp = base + (size_t)(row0 + ai * 128 + m * 16) * ld + col0;
;                 u32x4 w0, w1;
;                 w0.x = cvt_pk_bf16(acc[ai][0][m][0][0], acc[ai][0][m][0][1]); w0.y = cvt_pk_bf16(acc[ai][0][m][0][2], acc[ai][0][m][0][3]);
;                 w0.z = cvt_pk_bf16(acc[ai][0][m][1][0], acc[ai][0][m][1][1]); w0.w = cvt_pk_bf16(acc[ai][0][m][1][2], acc[ai][0][m][1][3]);
;                 w1.x = cvt_pk_bf16(acc[ai][1][m][0][0], acc[ai][1][m][0][1]); w1.y = cvt_pk_bf16(acc[ai][1][m][0][2], acc[ai][1][m][0][3]);
;                 w1.z = cvt_pk_bf16(acc[ai][1][m][1][0], acc[ai][1][m][1][1]); w1.w = cvt_pk_bf16(acc[ai][1][m][1][2], acc[ai][1][m][1][3]);
;                 st_wt16(rp, w0); st_wt16_o256(rp, w1);
;             }
.Lg1_fullepi:
	v_lshl_or_b32 v150, s38, 8, v146
	v_readlane_b32 s16, v254, 20
	v_ashrrev_i32_e32 v151, 31, v150
	v_readlane_b32 s17, v254, 21
	v_lshl_add_u32 v154, s6, 8, v144
	v_cvt_pk_bf16_f32 v124, v124, v125
	v_lshl_add_u64 v[150:151], v[150:151], 1, s[16:17]
	v_mad_i64_i32 v[152:153], s[16:17], v154, s37, v[150:151]
	v_cvt_pk_bf16_f32 v125, v126, v127
	v_cvt_pk_bf16_f32 v126, v120, v121
	v_cvt_pk_bf16_f32 v127, v122, v123
	global_store_dwordx4 v[152:153], v[124:127], off sc1
	s_nop 1
	v_cvt_pk_bf16_f32 v108, v108, v109
	v_cvt_pk_bf16_f32 v109, v110, v111
	v_cvt_pk_bf16_f32 v110, v104, v105
	v_cvt_pk_bf16_f32 v111, v106, v107
	global_store_dwordx4 v[152:153], v[108:111], off offset:256 sc1
	s_nop 1
	v_or_b32_e32 v104, 16, v154
	v_mad_i64_i32 v[108:109], s[16:17], v104, s37, v[150:151]
	v_cvt_pk_bf16_f32 v104, v116, v117
	v_cvt_pk_bf16_f32 v105, v118, v119
	v_cvt_pk_bf16_f32 v106, v112, v113
	v_cvt_pk_bf16_f32 v107, v114, v115
	global_store_dwordx4 v[108:109], v[104:107], off sc1
	s_nop 1
	v_cvt_pk_bf16_f32 v92, v92, v93
	v_cvt_pk_bf16_f32 v93, v94, v95
	v_cvt_pk_bf16_f32 v94, v88, v89
	v_cvt_pk_bf16_f32 v95, v90, v91
	global_store_dwordx4 v[108:109], v[92:95], off offset:256 sc1
	s_nop 1
	v_or_b32_e32 v88, 32, v154
	v_mad_i64_i32 v[92:93], s[16:17], v88, s37, v[150:151]
	v_cvt_pk_bf16_f32 v88, v100, v101
	v_cvt_pk_bf16_f32 v89, v102, v103
	v_cvt_pk_bf16_f32 v90, v96, v97
	v_cvt_pk_bf16_f32 v91, v98, v99
	global_store_dwordx4 v[92:93], v[88:91], off sc1
	s_nop 1
	v_cvt_pk_bf16_f32 v76, v76, v77
	v_cvt_pk_bf16_f32 v77, v78, v79
	v_cvt_pk_bf16_f32 v78, v72, v73
	v_cvt_pk_bf16_f32 v79, v74, v75
	global_store_dwordx4 v[92:93], v[76:79], off offset:256 sc1
	s_nop 1
	v_or_b32_e32 v72, 48, v154
	v_mad_i64_i32 v[76:77], s[16:17], v72, s37, v[150:151]
	v_cvt_pk_bf16_f32 v72, v84, v85
	v_cvt_pk_bf16_f32 v73, v86, v87
	v_cvt_pk_bf16_f32 v74, v80, v81
	v_cvt_pk_bf16_f32 v75, v82, v83
	global_store_dwordx4 v[76:77], v[72:75], off sc1
	s_nop 1
	v_cvt_pk_bf16_f32 v68, v68, v69
	v_cvt_pk_bf16_f32 v69, v70, v71
	v_cvt_pk_bf16_f32 v70, v64, v65
	v_cvt_pk_bf16_f32 v71, v66, v67
	global_store_dwordx4 v[76:77], v[68:71], off offset:256 sc1
	s_nop 1
	v_add_u32_e32 v64, 0x80, v154
	v_mad_i64_i32 v[64:65], s[16:17], v64, s37, v[150:151]
	v_cvt_pk_bf16_f32 v60, v60, v61
	v_cvt_pk_bf16_f32 v61, v62, v63
	v_cvt_pk_bf16_f32 v62, v56, v57
	v_cvt_pk_bf16_f32 v63, v58, v59
	global_store_dwordx4 v[64:65], v[60:63], off sc1
	s_nop 1
	v_cvt_pk_bf16_f32 v44, v44, v45
	v_cvt_pk_bf16_f32 v45, v46, v47
	v_cvt_pk_bf16_f32 v46, v40, v41
	v_cvt_pk_bf16_f32 v47, v42, v43
	global_store_dwordx4 v[64:65], v[44:47], off offset:256 sc1
	s_nop 1
	v_add_u32_e32 v40, 0x90, v154
	v_mad_i64_i32 v[44:45], s[16:17], v40, s37, v[150:151]
	v_cvt_pk_bf16_f32 v40, v52, v53
	v_cvt_pk_bf16_f32 v41, v54, v55
	v_cvt_pk_bf16_f32 v42, v48, v49
	v_cvt_pk_bf16_f32 v43, v50, v51
	global_store_dwordx4 v[44:45], v[40:43], off sc1
	s_nop 1
	v_cvt_pk_bf16_f32 v28, v28, v29
	v_cvt_pk_bf16_f32 v29, v30, v31
	v_cvt_pk_bf16_f32 v30, v24, v25
	v_cvt_pk_bf16_f32 v31, v26, v27
	global_store_dwordx4 v[44:45], v[28:31], off offset:256 sc1
	s_nop 1
	v_add_u32_e32 v24, 0xa0, v154
	v_mad_i64_i32 v[28:29], s[16:17], v24, s37, v[150:151]
	v_cvt_pk_bf16_f32 v24, v36, v37
	v_cvt_pk_bf16_f32 v25, v38, v39
	v_cvt_pk_bf16_f32 v26, v32, v33
	v_cvt_pk_bf16_f32 v27, v34, v35
	global_store_dwordx4 v[28:29], v[24:27], off sc1
	s_nop 1
	v_cvt_pk_bf16_f32 v12, v12, v13
	v_cvt_pk_bf16_f32 v13, v14, v15
	v_cvt_pk_bf16_f32 v14, v8, v9
	v_cvt_pk_bf16_f32 v15, v10, v11
	global_store_dwordx4 v[28:29], v[12:15], off offset:256 sc1
	s_nop 1
	v_add_u32_e32 v8, 0xb0, v154
	v_mad_i64_i32 v[12:13], s[16:17], v8, s37, v[150:151]
	v_cvt_pk_bf16_f32 v8, v20, v21
	v_cvt_pk_bf16_f32 v9, v22, v23
	v_cvt_pk_bf16_f32 v10, v16, v17
	v_cvt_pk_bf16_f32 v11, v18, v19
	global_store_dwordx4 v[12:13], v[8:11], off sc1
	s_nop 1
	v_cvt_pk_bf16_f32 v4, v4, v5
	v_cvt_pk_bf16_f32 v5, v6, v7
	v_cvt_pk_bf16_f32 v6, v0, v1
	v_cvt_pk_bf16_f32 v7, v2, v3
	global_store_dwordx4 v[12:13], v[4:7], off offset:256 sc1
	s_nop 1
	s_and_b64 vcc, exec, s[2:3]
	s_mov_b32 s38, s8
	s_mov_b32 s6, s10
	s_mov_b64 s[18:19], s[14:15]
	s_mov_b64 s[16:17], s[12:13]
	s_cbranch_vccz .LBB0_115
	s_waitcnt vmcnt(0)
	s_cmpk_gt_u32 s22, 0xff
	s_cbranch_scc1 .LBB0_122
	s_barrier
